# P0: silu(c) staging loop unrolled so its 32 dependent global loads are issued together
# speedup vs baseline: 1.0474x; 1.0043x over previous
; #define LAS __attribute__((address_space(3)))
; __device__ __forceinline__ void phase0(const Args& a, LAS unsigned char* lds, int G, int wv) {
;     int tid_; asm volatile("v_mbcnt_lo_u32_b32 %0, -1, 0\n\tv_mbcnt_hi_u32_b32 %0, -1, %0" : "=v"(tid_)); tid_ |= (wv << 6); const int tid = tid_, lane = tid & 63, wave = __builtin_amdgcn_readfirstlane(tid >> 6);
;     const int gw = blockIdx.x * 8 + wave, NGW = G * 8;
;     LAS float* SC = (LAS float*)lds;
;     LAS float* scr = (LAS float*)(lds + 65536 + wave * 8448);
;     const float* cin = (const float*)a.in[1];
;     for (int idx = tid; idx < 8 * 2048; idx += 512) { const int b = idx >> 11, k = idx & 2047; const float v = cin[idx]; SC[k * 8 + b] = v / (1.0f + __expf(-v)); }
.LBB0_15:
	s_and_b32 s90, s84, 0xffffffc0
	s_cmp_lt_i32 s82, 1
	s_cselect_b64 s[2:3], -1, 0
	s_cmp_gt_i32 s83, 0
	s_cselect_b64 s[4:5], -1, 0
	s_and_b64 s[20:21], s[2:3], s[4:5]
	s_andn2_b64 vcc, exec, s[20:21]
	s_cbranch_vccnz .LBB0_125
	s_load_dwordx4 s[16:19], s[0:1], 0x8
	s_load_dwordx2 s[24:25], s[0:1], 0x18
	s_load_dwordx2 s[2:3], s[0:1], 0x30
	s_load_dwordx2 s[22:23], s[0:1], 0x88
	s_load_dwordx4 s[12:15], s[0:1], 0x78
	s_load_dwordx8 s[4:11], s[0:1], 0x58
	s_waitcnt lgkmcnt(0)
	s_barrier
	v_mbcnt_lo_u32_b32 v40, -1, 0
	v_mbcnt_hi_u32_b32 v40, -1, v40
	s_movk_i32 s26, 0x4000
	v_or_b32_e32 v32, s90, v40
	v_cmp_gt_i32_e32 vcc, s26, v32
	v_readfirstlane_b32 s30, v32
	s_and_saveexec_b64 s[26:27], vcc
	s_cbranch_execz .LBB0_19
	v_lshlrev_b32_e32 v2, 2, v32
	v_lshlrev_b32_e32 v5, 5, v32
	s_mov_b64 s[28:29], s[16:17]
	global_load_dword v200, v2, s[28:29]
	s_add_u32 s28, s28, 0x800
	s_addc_u32 s29, s29, 0
	global_load_dword v201, v2, s[28:29]
	s_add_u32 s28, s28, 0x800
	s_addc_u32 s29, s29, 0
	global_load_dword v202, v2, s[28:29]
	s_add_u32 s28, s28, 0x800
	s_addc_u32 s29, s29, 0
	global_load_dword v203, v2, s[28:29]
	s_add_u32 s28, s28, 0x800
	s_addc_u32 s29, s29, 0
	global_load_dword v204, v2, s[28:29]
	s_add_u32 s28, s28, 0x800
	s_addc_u32 s29, s29, 0
	global_load_dword v205, v2, s[28:29]
	s_add_u32 s28, s28, 0x800
	s_addc_u32 s29, s29, 0
	global_load_dword v206, v2, s[28:29]
	s_add_u32 s28, s28, 0x800
	s_addc_u32 s29, s29, 0
	global_load_dword v207, v2, s[28:29]
	s_add_u32 s28, s28, 0x800
	s_addc_u32 s29, s29, 0
	global_load_dword v208, v2, s[28:29]
	s_add_u32 s28, s28, 0x800
	s_addc_u32 s29, s29, 0
	global_load_dword v209, v2, s[28:29]
	s_add_u32 s28, s28, 0x800
	s_addc_u32 s29, s29, 0
	global_load_dword v210, v2, s[28:29]
	s_add_u32 s28, s28, 0x800
	s_addc_u32 s29, s29, 0
	global_load_dword v211, v2, s[28:29]
	s_add_u32 s28, s28, 0x800
	s_addc_u32 s29, s29, 0
	global_load_dword v212, v2, s[28:29]
	s_add_u32 s28, s28, 0x800
	s_addc_u32 s29, s29, 0
	global_load_dword v213, v2, s[28:29]
	s_add_u32 s28, s28, 0x800
	s_addc_u32 s29, s29, 0
	global_load_dword v214, v2, s[28:29]
	s_add_u32 s28, s28, 0x800
	s_addc_u32 s29, s29, 0
	global_load_dword v215, v2, s[28:29]
	s_add_u32 s28, s28, 0x800
	s_addc_u32 s29, s29, 0
	global_load_dword v216, v2, s[28:29]
	s_add_u32 s28, s28, 0x800
	s_addc_u32 s29, s29, 0
	global_load_dword v217, v2, s[28:29]
	s_add_u32 s28, s28, 0x800
	s_addc_u32 s29, s29, 0
	global_load_dword v218, v2, s[28:29]
	s_add_u32 s28, s28, 0x800
	s_addc_u32 s29, s29, 0
	global_load_dword v219, v2, s[28:29]
	s_add_u32 s28, s28, 0x800
	s_addc_u32 s29, s29, 0
	global_load_dword v220, v2, s[28:29]
	s_add_u32 s28, s28, 0x800
	s_addc_u32 s29, s29, 0
	global_load_dword v221, v2, s[28:29]
	s_add_u32 s28, s28, 0x800
	s_addc_u32 s29, s29, 0
	global_load_dword v222, v2, s[28:29]
	s_add_u32 s28, s28, 0x800
	s_addc_u32 s29, s29, 0
	global_load_dword v223, v2, s[28:29]
	s_add_u32 s28, s28, 0x800
	s_addc_u32 s29, s29, 0
	global_load_dword v224, v2, s[28:29]
	s_add_u32 s28, s28, 0x800
	s_addc_u32 s29, s29, 0
	global_load_dword v225, v2, s[28:29]
	s_add_u32 s28, s28, 0x800
	s_addc_u32 s29, s29, 0
	global_load_dword v226, v2, s[28:29]
	s_add_u32 s28, s28, 0x800
	s_addc_u32 s29, s29, 0
	global_load_dword v227, v2, s[28:29]
	s_add_u32 s28, s28, 0x800
	s_addc_u32 s29, s29, 0
	global_load_dword v228, v2, s[28:29]
	s_add_u32 s28, s28, 0x800
	s_addc_u32 s29, s29, 0
	global_load_dword v229, v2, s[28:29]
	s_add_u32 s28, s28, 0x800
	s_addc_u32 s29, s29, 0
	global_load_dword v230, v2, s[28:29]
	s_add_u32 s28, s28, 0x800
	s_addc_u32 s29, s29, 0
	global_load_dword v231, v2, s[28:29]
	s_add_u32 s28, s28, 0x800
	s_addc_u32 s29, s29, 0
	s_waitcnt vmcnt(31)
	v_mul_f32_e32 v7, 0xbfb8aa3b, v200
	v_exp_f32_e32 v7, v7
	s_nop 0
	v_add_f32_e32 v6, 1.0, v7
	v_div_scale_f32 v7, s[34:35], v6, v6, v200
	v_rcp_f32_e32 v8, v7
	v_div_scale_f32 v9, vcc, v200, v6, v200
	v_fma_f32 v10, -v7, v8, 1.0
	v_fmac_f32_e32 v8, v10, v8
	v_mul_f32_e32 v10, v9, v8
	v_fma_f32 v11, -v7, v10, v9
	v_fmac_f32_e32 v10, v11, v8
	v_fma_f32 v7, -v7, v10, v9
	v_div_fmas_f32 v7, v7, v8, v10
	v_div_fixup_f32 v200, v7, v6, v200
	ds_write_b32 v5, v200
	s_waitcnt vmcnt(30)
	v_mul_f32_e32 v7, 0xbfb8aa3b, v201
	v_exp_f32_e32 v7, v7
	s_nop 0
	v_add_f32_e32 v6, 1.0, v7
	v_div_scale_f32 v7, s[34:35], v6, v6, v201
	v_rcp_f32_e32 v8, v7
	v_div_scale_f32 v9, vcc, v201, v6, v201
	v_fma_f32 v10, -v7, v8, 1.0
	v_fmac_f32_e32 v8, v10, v8
	v_mul_f32_e32 v10, v9, v8
	v_fma_f32 v11, -v7, v10, v9
	v_fmac_f32_e32 v10, v11, v8
	v_fma_f32 v7, -v7, v10, v9
	v_div_fmas_f32 v7, v7, v8, v10
	v_div_fixup_f32 v201, v7, v6, v201
	ds_write_b32 v5, v201 offset:16384
	s_waitcnt vmcnt(29)
	v_mul_f32_e32 v7, 0xbfb8aa3b, v202
	v_exp_f32_e32 v7, v7
	s_nop 0
	v_add_f32_e32 v6, 1.0, v7
	v_div_scale_f32 v7, s[34:35], v6, v6, v202
	v_rcp_f32_e32 v8, v7
	v_div_scale_f32 v9, vcc, v202, v6, v202
	v_fma_f32 v10, -v7, v8, 1.0
	v_fmac_f32_e32 v8, v10, v8
	v_mul_f32_e32 v10, v9, v8
	v_fma_f32 v11, -v7, v10, v9
	v_fmac_f32_e32 v10, v11, v8
	v_fma_f32 v7, -v7, v10, v9
	v_div_fmas_f32 v7, v7, v8, v10
	v_div_fixup_f32 v202, v7, v6, v202
	ds_write_b32 v5, v202 offset:32768
	s_waitcnt vmcnt(28)
	v_mul_f32_e32 v7, 0xbfb8aa3b, v203
	v_exp_f32_e32 v7, v7
	s_nop 0
	v_add_f32_e32 v6, 1.0, v7
	v_div_scale_f32 v7, s[34:35], v6, v6, v203
	v_rcp_f32_e32 v8, v7
	v_div_scale_f32 v9, vcc, v203, v6, v203
	v_fma_f32 v10, -v7, v8, 1.0
	v_fmac_f32_e32 v8, v10, v8
	v_mul_f32_e32 v10, v9, v8
	v_fma_f32 v11, -v7, v10, v9
	v_fmac_f32_e32 v10, v11, v8
	v_fma_f32 v7, -v7, v10, v9
	v_div_fmas_f32 v7, v7, v8, v10
	v_div_fixup_f32 v203, v7, v6, v203
	ds_write_b32 v5, v203 offset:49152
	s_waitcnt vmcnt(27)
; __device__ __forceinline__ void phase0(const Args& a, LAS unsigned char* lds, int G, int wv) {
;     ...
;     for (int idx = tid; idx < 8 * 2048; idx += 512) { const int b = idx >> 11, k = idx & 2047; const float v = cin[idx]; SC[k * 8 + b] = v / (1.0f + __expf(-v)); }
	v_mul_f32_e32 v7, 0xbfb8aa3b, v204
	v_exp_f32_e32 v7, v7
	s_nop 0
	v_add_f32_e32 v6, 1.0, v7
	v_div_scale_f32 v7, s[34:35], v6, v6, v204
	v_rcp_f32_e32 v8, v7
	v_div_scale_f32 v9, vcc, v204, v6, v204
	v_fma_f32 v10, -v7, v8, 1.0
	v_fmac_f32_e32 v8, v10, v8
	v_mul_f32_e32 v10, v9, v8
	v_fma_f32 v11, -v7, v10, v9
	v_fmac_f32_e32 v10, v11, v8
	v_fma_f32 v7, -v7, v10, v9
	v_div_fmas_f32 v7, v7, v8, v10
	v_div_fixup_f32 v204, v7, v6, v204
	ds_write_b32 v5, v204 offset:4
	s_waitcnt vmcnt(26)
	v_mul_f32_e32 v7, 0xbfb8aa3b, v205
	v_exp_f32_e32 v7, v7
	s_nop 0
	v_add_f32_e32 v6, 1.0, v7
	v_div_scale_f32 v7, s[34:35], v6, v6, v205
	v_rcp_f32_e32 v8, v7
	v_div_scale_f32 v9, vcc, v205, v6, v205
	v_fma_f32 v10, -v7, v8, 1.0
	v_fmac_f32_e32 v8, v10, v8
	v_mul_f32_e32 v10, v9, v8
	v_fma_f32 v11, -v7, v10, v9
	v_fmac_f32_e32 v10, v11, v8
	v_fma_f32 v7, -v7, v10, v9
	v_div_fmas_f32 v7, v7, v8, v10
	v_div_fixup_f32 v205, v7, v6, v205
	ds_write_b32 v5, v205 offset:16388
	s_waitcnt vmcnt(25)
	v_mul_f32_e32 v7, 0xbfb8aa3b, v206
	v_exp_f32_e32 v7, v7
	s_nop 0
	v_add_f32_e32 v6, 1.0, v7
	v_div_scale_f32 v7, s[34:35], v6, v6, v206
	v_rcp_f32_e32 v8, v7
	v_div_scale_f32 v9, vcc, v206, v6, v206
	v_fma_f32 v10, -v7, v8, 1.0
	v_fmac_f32_e32 v8, v10, v8
	v_mul_f32_e32 v10, v9, v8
	v_fma_f32 v11, -v7, v10, v9
	v_fmac_f32_e32 v10, v11, v8
	v_fma_f32 v7, -v7, v10, v9
	v_div_fmas_f32 v7, v7, v8, v10
	v_div_fixup_f32 v206, v7, v6, v206
	ds_write_b32 v5, v206 offset:32772
	s_waitcnt vmcnt(24)
	v_mul_f32_e32 v7, 0xbfb8aa3b, v207
	v_exp_f32_e32 v7, v7
	s_nop 0
	v_add_f32_e32 v6, 1.0, v7
	v_div_scale_f32 v7, s[34:35], v6, v6, v207
	v_rcp_f32_e32 v8, v7
	v_div_scale_f32 v9, vcc, v207, v6, v207
	v_fma_f32 v10, -v7, v8, 1.0
	v_fmac_f32_e32 v8, v10, v8
	v_mul_f32_e32 v10, v9, v8
	v_fma_f32 v11, -v7, v10, v9
	v_fmac_f32_e32 v10, v11, v8
	v_fma_f32 v7, -v7, v10, v9
	v_div_fmas_f32 v7, v7, v8, v10
	v_div_fixup_f32 v207, v7, v6, v207
	ds_write_b32 v5, v207 offset:49156
	s_waitcnt vmcnt(23)
	v_mul_f32_e32 v7, 0xbfb8aa3b, v208
	v_exp_f32_e32 v7, v7
	s_nop 0
	v_add_f32_e32 v6, 1.0, v7
	v_div_scale_f32 v7, s[34:35], v6, v6, v208
	v_rcp_f32_e32 v8, v7
	v_div_scale_f32 v9, vcc, v208, v6, v208
	v_fma_f32 v10, -v7, v8, 1.0
	v_fmac_f32_e32 v8, v10, v8
	v_mul_f32_e32 v10, v9, v8
	v_fma_f32 v11, -v7, v10, v9
	v_fmac_f32_e32 v10, v11, v8
	v_fma_f32 v7, -v7, v10, v9
	v_div_fmas_f32 v7, v7, v8, v10
	v_div_fixup_f32 v208, v7, v6, v208
	ds_write_b32 v5, v208 offset:8
	s_waitcnt vmcnt(22)
	v_mul_f32_e32 v7, 0xbfb8aa3b, v209
	v_exp_f32_e32 v7, v7
	s_nop 0
	v_add_f32_e32 v6, 1.0, v7
	v_div_scale_f32 v7, s[34:35], v6, v6, v209
	v_rcp_f32_e32 v8, v7
	v_div_scale_f32 v9, vcc, v209, v6, v209
	v_fma_f32 v10, -v7, v8, 1.0
	v_fmac_f32_e32 v8, v10, v8
	v_mul_f32_e32 v10, v9, v8
	v_fma_f32 v11, -v7, v10, v9
	v_fmac_f32_e32 v10, v11, v8
	v_fma_f32 v7, -v7, v10, v9
	v_div_fmas_f32 v7, v7, v8, v10
	v_div_fixup_f32 v209, v7, v6, v209
	ds_write_b32 v5, v209 offset:16392
	s_waitcnt vmcnt(21)
	v_mul_f32_e32 v7, 0xbfb8aa3b, v210
	v_exp_f32_e32 v7, v7
	s_nop 0
	v_add_f32_e32 v6, 1.0, v7
	v_div_scale_f32 v7, s[34:35], v6, v6, v210
	v_rcp_f32_e32 v8, v7
	v_div_scale_f32 v9, vcc, v210, v6, v210
	v_fma_f32 v10, -v7, v8, 1.0
	v_fmac_f32_e32 v8, v10, v8
	v_mul_f32_e32 v10, v9, v8
	v_fma_f32 v11, -v7, v10, v9
	v_fmac_f32_e32 v10, v11, v8
	v_fma_f32 v7, -v7, v10, v9
	v_div_fmas_f32 v7, v7, v8, v10
	v_div_fixup_f32 v210, v7, v6, v210
	ds_write_b32 v5, v210 offset:32776
	s_waitcnt vmcnt(20)
	v_mul_f32_e32 v7, 0xbfb8aa3b, v211
	v_exp_f32_e32 v7, v7
	s_nop 0
	v_add_f32_e32 v6, 1.0, v7
	v_div_scale_f32 v7, s[34:35], v6, v6, v211
	v_rcp_f32_e32 v8, v7
	v_div_scale_f32 v9, vcc, v211, v6, v211
	v_fma_f32 v10, -v7, v8, 1.0
	v_fmac_f32_e32 v8, v10, v8
	v_mul_f32_e32 v10, v9, v8
	v_fma_f32 v11, -v7, v10, v9
	v_fmac_f32_e32 v10, v11, v8
	v_fma_f32 v7, -v7, v10, v9
	v_div_fmas_f32 v7, v7, v8, v10
	v_div_fixup_f32 v211, v7, v6, v211
	ds_write_b32 v5, v211 offset:49160
	s_waitcnt vmcnt(19)
	v_mul_f32_e32 v7, 0xbfb8aa3b, v212
	v_exp_f32_e32 v7, v7
	s_nop 0
	v_add_f32_e32 v6, 1.0, v7
	v_div_scale_f32 v7, s[34:35], v6, v6, v212
	v_rcp_f32_e32 v8, v7
	v_div_scale_f32 v9, vcc, v212, v6, v212
	v_fma_f32 v10, -v7, v8, 1.0
	v_fmac_f32_e32 v8, v10, v8
	v_mul_f32_e32 v10, v9, v8
	v_fma_f32 v11, -v7, v10, v9
	v_fmac_f32_e32 v10, v11, v8
	v_fma_f32 v7, -v7, v10, v9
	v_div_fmas_f32 v7, v7, v8, v10
	v_div_fixup_f32 v212, v7, v6, v212
	ds_write_b32 v5, v212 offset:12
	s_waitcnt vmcnt(18)
	v_mul_f32_e32 v7, 0xbfb8aa3b, v213
	v_exp_f32_e32 v7, v7
	s_nop 0
	v_add_f32_e32 v6, 1.0, v7
	v_div_scale_f32 v7, s[34:35], v6, v6, v213
	v_rcp_f32_e32 v8, v7
	v_div_scale_f32 v9, vcc, v213, v6, v213
	v_fma_f32 v10, -v7, v8, 1.0
	v_fmac_f32_e32 v8, v10, v8
	v_mul_f32_e32 v10, v9, v8
	v_fma_f32 v11, -v7, v10, v9
	v_fmac_f32_e32 v10, v11, v8
	v_fma_f32 v7, -v7, v10, v9
	v_div_fmas_f32 v7, v7, v8, v10
	v_div_fixup_f32 v213, v7, v6, v213
	ds_write_b32 v5, v213 offset:16396
	s_waitcnt vmcnt(17)
	v_mul_f32_e32 v7, 0xbfb8aa3b, v214
	v_exp_f32_e32 v7, v7
	s_nop 0
	v_add_f32_e32 v6, 1.0, v7
	v_div_scale_f32 v7, s[34:35], v6, v6, v214
	v_rcp_f32_e32 v8, v7
	v_div_scale_f32 v9, vcc, v214, v6, v214
	v_fma_f32 v10, -v7, v8, 1.0
	v_fmac_f32_e32 v8, v10, v8
	v_mul_f32_e32 v10, v9, v8
	v_fma_f32 v11, -v7, v10, v9
	v_fmac_f32_e32 v10, v11, v8
	v_fma_f32 v7, -v7, v10, v9
	v_div_fmas_f32 v7, v7, v8, v10
	v_div_fixup_f32 v214, v7, v6, v214
	ds_write_b32 v5, v214 offset:32780
	s_waitcnt vmcnt(16)
; __device__ __forceinline__ void phase0(const Args& a, LAS unsigned char* lds, int G, int wv) {
;     ...
;     for (int idx = tid; idx < 8 * 2048; idx += 512) { const int b = idx >> 11, k = idx & 2047; const float v = cin[idx]; SC[k * 8 + b] = v / (1.0f + __expf(-v)); }
	v_mul_f32_e32 v7, 0xbfb8aa3b, v215
	v_exp_f32_e32 v7, v7
	s_nop 0
	v_add_f32_e32 v6, 1.0, v7
	v_div_scale_f32 v7, s[34:35], v6, v6, v215
	v_rcp_f32_e32 v8, v7
	v_div_scale_f32 v9, vcc, v215, v6, v215
	v_fma_f32 v10, -v7, v8, 1.0
	v_fmac_f32_e32 v8, v10, v8
	v_mul_f32_e32 v10, v9, v8
	v_fma_f32 v11, -v7, v10, v9
	v_fmac_f32_e32 v10, v11, v8
	v_fma_f32 v7, -v7, v10, v9
	v_div_fmas_f32 v7, v7, v8, v10
	v_div_fixup_f32 v215, v7, v6, v215
	ds_write_b32 v5, v215 offset:49164
	s_waitcnt vmcnt(15)
	v_mul_f32_e32 v7, 0xbfb8aa3b, v216
	v_exp_f32_e32 v7, v7
	s_nop 0
	v_add_f32_e32 v6, 1.0, v7
	v_div_scale_f32 v7, s[34:35], v6, v6, v216
	v_rcp_f32_e32 v8, v7
	v_div_scale_f32 v9, vcc, v216, v6, v216
	v_fma_f32 v10, -v7, v8, 1.0
	v_fmac_f32_e32 v8, v10, v8
	v_mul_f32_e32 v10, v9, v8
	v_fma_f32 v11, -v7, v10, v9
	v_fmac_f32_e32 v10, v11, v8
	v_fma_f32 v7, -v7, v10, v9
	v_div_fmas_f32 v7, v7, v8, v10
	v_div_fixup_f32 v216, v7, v6, v216
	ds_write_b32 v5, v216 offset:16
	s_waitcnt vmcnt(14)
	v_mul_f32_e32 v7, 0xbfb8aa3b, v217
	v_exp_f32_e32 v7, v7
	s_nop 0
	v_add_f32_e32 v6, 1.0, v7
	v_div_scale_f32 v7, s[34:35], v6, v6, v217
	v_rcp_f32_e32 v8, v7
	v_div_scale_f32 v9, vcc, v217, v6, v217
	v_fma_f32 v10, -v7, v8, 1.0
	v_fmac_f32_e32 v8, v10, v8
	v_mul_f32_e32 v10, v9, v8
	v_fma_f32 v11, -v7, v10, v9
	v_fmac_f32_e32 v10, v11, v8
	v_fma_f32 v7, -v7, v10, v9
	v_div_fmas_f32 v7, v7, v8, v10
	v_div_fixup_f32 v217, v7, v6, v217
	ds_write_b32 v5, v217 offset:16400
	s_waitcnt vmcnt(13)
	v_mul_f32_e32 v7, 0xbfb8aa3b, v218
	v_exp_f32_e32 v7, v7
	s_nop 0
	v_add_f32_e32 v6, 1.0, v7
	v_div_scale_f32 v7, s[34:35], v6, v6, v218
	v_rcp_f32_e32 v8, v7
	v_div_scale_f32 v9, vcc, v218, v6, v218
	v_fma_f32 v10, -v7, v8, 1.0
	v_fmac_f32_e32 v8, v10, v8
	v_mul_f32_e32 v10, v9, v8
	v_fma_f32 v11, -v7, v10, v9
	v_fmac_f32_e32 v10, v11, v8
	v_fma_f32 v7, -v7, v10, v9
	v_div_fmas_f32 v7, v7, v8, v10
	v_div_fixup_f32 v218, v7, v6, v218
	ds_write_b32 v5, v218 offset:32784
	s_waitcnt vmcnt(12)
	v_mul_f32_e32 v7, 0xbfb8aa3b, v219
	v_exp_f32_e32 v7, v7
	s_nop 0
	v_add_f32_e32 v6, 1.0, v7
	v_div_scale_f32 v7, s[34:35], v6, v6, v219
	v_rcp_f32_e32 v8, v7
	v_div_scale_f32 v9, vcc, v219, v6, v219
	v_fma_f32 v10, -v7, v8, 1.0
	v_fmac_f32_e32 v8, v10, v8
	v_mul_f32_e32 v10, v9, v8
	v_fma_f32 v11, -v7, v10, v9
	v_fmac_f32_e32 v10, v11, v8
	v_fma_f32 v7, -v7, v10, v9
	v_div_fmas_f32 v7, v7, v8, v10
	v_div_fixup_f32 v219, v7, v6, v219
	ds_write_b32 v5, v219 offset:49168
	s_waitcnt vmcnt(11)
	v_mul_f32_e32 v7, 0xbfb8aa3b, v220
	v_exp_f32_e32 v7, v7
	s_nop 0
	v_add_f32_e32 v6, 1.0, v7
	v_div_scale_f32 v7, s[34:35], v6, v6, v220
	v_rcp_f32_e32 v8, v7
	v_div_scale_f32 v9, vcc, v220, v6, v220
	v_fma_f32 v10, -v7, v8, 1.0
	v_fmac_f32_e32 v8, v10, v8
	v_mul_f32_e32 v10, v9, v8
	v_fma_f32 v11, -v7, v10, v9
	v_fmac_f32_e32 v10, v11, v8
	v_fma_f32 v7, -v7, v10, v9
	v_div_fmas_f32 v7, v7, v8, v10
	v_div_fixup_f32 v220, v7, v6, v220
	ds_write_b32 v5, v220 offset:20
	s_waitcnt vmcnt(10)
	v_mul_f32_e32 v7, 0xbfb8aa3b, v221
	v_exp_f32_e32 v7, v7
	s_nop 0
	v_add_f32_e32 v6, 1.0, v7
	v_div_scale_f32 v7, s[34:35], v6, v6, v221
	v_rcp_f32_e32 v8, v7
	v_div_scale_f32 v9, vcc, v221, v6, v221
	v_fma_f32 v10, -v7, v8, 1.0
	v_fmac_f32_e32 v8, v10, v8
	v_mul_f32_e32 v10, v9, v8
	v_fma_f32 v11, -v7, v10, v9
	v_fmac_f32_e32 v10, v11, v8
	v_fma_f32 v7, -v7, v10, v9
	v_div_fmas_f32 v7, v7, v8, v10
	v_div_fixup_f32 v221, v7, v6, v221
	ds_write_b32 v5, v221 offset:16404
	s_waitcnt vmcnt(9)
	v_mul_f32_e32 v7, 0xbfb8aa3b, v222
	v_exp_f32_e32 v7, v7
	s_nop 0
	v_add_f32_e32 v6, 1.0, v7
	v_div_scale_f32 v7, s[34:35], v6, v6, v222
	v_rcp_f32_e32 v8, v7
	v_div_scale_f32 v9, vcc, v222, v6, v222
	v_fma_f32 v10, -v7, v8, 1.0
	v_fmac_f32_e32 v8, v10, v8
	v_mul_f32_e32 v10, v9, v8
	v_fma_f32 v11, -v7, v10, v9
	v_fmac_f32_e32 v10, v11, v8
	v_fma_f32 v7, -v7, v10, v9
	v_div_fmas_f32 v7, v7, v8, v10
	v_div_fixup_f32 v222, v7, v6, v222
	ds_write_b32 v5, v222 offset:32788
	s_waitcnt vmcnt(8)
; __device__ __forceinline__ void phase0(const Args& a, LAS unsigned char* lds, int G, int wv) {
;     ...
;     for (int idx = tid; idx < 8 * 2048; idx += 512) { const int b = idx >> 11, k = idx & 2047; const float v = cin[idx]; SC[k * 8 + b] = v / (1.0f + __expf(-v)); }
	v_mul_f32_e32 v7, 0xbfb8aa3b, v223
	v_exp_f32_e32 v7, v7
	s_nop 0
	v_add_f32_e32 v6, 1.0, v7
	v_div_scale_f32 v7, s[34:35], v6, v6, v223
	v_rcp_f32_e32 v8, v7
	v_div_scale_f32 v9, vcc, v223, v6, v223
	v_fma_f32 v10, -v7, v8, 1.0
	v_fmac_f32_e32 v8, v10, v8
	v_mul_f32_e32 v10, v9, v8
	v_fma_f32 v11, -v7, v10, v9
	v_fmac_f32_e32 v10, v11, v8
	v_fma_f32 v7, -v7, v10, v9
	v_div_fmas_f32 v7, v7, v8, v10
	v_div_fixup_f32 v223, v7, v6, v223
	ds_write_b32 v5, v223 offset:49172
	s_waitcnt vmcnt(7)
	v_mul_f32_e32 v7, 0xbfb8aa3b, v224
	v_exp_f32_e32 v7, v7
	s_nop 0
	v_add_f32_e32 v6, 1.0, v7
	v_div_scale_f32 v7, s[34:35], v6, v6, v224
	v_rcp_f32_e32 v8, v7
	v_div_scale_f32 v9, vcc, v224, v6, v224
	v_fma_f32 v10, -v7, v8, 1.0
	v_fmac_f32_e32 v8, v10, v8
	v_mul_f32_e32 v10, v9, v8
	v_fma_f32 v11, -v7, v10, v9
	v_fmac_f32_e32 v10, v11, v8
	v_fma_f32 v7, -v7, v10, v9
	v_div_fmas_f32 v7, v7, v8, v10
	v_div_fixup_f32 v224, v7, v6, v224
	ds_write_b32 v5, v224 offset:24
	s_waitcnt vmcnt(6)
	v_mul_f32_e32 v7, 0xbfb8aa3b, v225
	v_exp_f32_e32 v7, v7
	s_nop 0
	v_add_f32_e32 v6, 1.0, v7
	v_div_scale_f32 v7, s[34:35], v6, v6, v225
	v_rcp_f32_e32 v8, v7
	v_div_scale_f32 v9, vcc, v225, v6, v225
	v_fma_f32 v10, -v7, v8, 1.0
	v_fmac_f32_e32 v8, v10, v8
	v_mul_f32_e32 v10, v9, v8
	v_fma_f32 v11, -v7, v10, v9
	v_fmac_f32_e32 v10, v11, v8
	v_fma_f32 v7, -v7, v10, v9
	v_div_fmas_f32 v7, v7, v8, v10
	v_div_fixup_f32 v225, v7, v6, v225
	ds_write_b32 v5, v225 offset:16408
	s_waitcnt vmcnt(5)
	v_mul_f32_e32 v7, 0xbfb8aa3b, v226
	v_exp_f32_e32 v7, v7
	s_nop 0
	v_add_f32_e32 v6, 1.0, v7
	v_div_scale_f32 v7, s[34:35], v6, v6, v226
	v_rcp_f32_e32 v8, v7
	v_div_scale_f32 v9, vcc, v226, v6, v226
	v_fma_f32 v10, -v7, v8, 1.0
	v_fmac_f32_e32 v8, v10, v8
	v_mul_f32_e32 v10, v9, v8
	v_fma_f32 v11, -v7, v10, v9
	v_fmac_f32_e32 v10, v11, v8
	v_fma_f32 v7, -v7, v10, v9
	v_div_fmas_f32 v7, v7, v8, v10
	v_div_fixup_f32 v226, v7, v6, v226
	ds_write_b32 v5, v226 offset:32792
	s_waitcnt vmcnt(4)
	v_mul_f32_e32 v7, 0xbfb8aa3b, v227
	v_exp_f32_e32 v7, v7
	s_nop 0
	v_add_f32_e32 v6, 1.0, v7
	v_div_scale_f32 v7, s[34:35], v6, v6, v227
	v_rcp_f32_e32 v8, v7
	v_div_scale_f32 v9, vcc, v227, v6, v227
	v_fma_f32 v10, -v7, v8, 1.0
	v_fmac_f32_e32 v8, v10, v8
	v_mul_f32_e32 v10, v9, v8
	v_fma_f32 v11, -v7, v10, v9
	v_fmac_f32_e32 v10, v11, v8
	v_fma_f32 v7, -v7, v10, v9
	v_div_fmas_f32 v7, v7, v8, v10
	v_div_fixup_f32 v227, v7, v6, v227
	ds_write_b32 v5, v227 offset:49176
	s_waitcnt vmcnt(3)
	v_mul_f32_e32 v7, 0xbfb8aa3b, v228
	v_exp_f32_e32 v7, v7
	s_nop 0
	v_add_f32_e32 v6, 1.0, v7
	v_div_scale_f32 v7, s[34:35], v6, v6, v228
	v_rcp_f32_e32 v8, v7
	v_div_scale_f32 v9, vcc, v228, v6, v228
	v_fma_f32 v10, -v7, v8, 1.0
	v_fmac_f32_e32 v8, v10, v8
	v_mul_f32_e32 v10, v9, v8
	v_fma_f32 v11, -v7, v10, v9
	v_fmac_f32_e32 v10, v11, v8
	v_fma_f32 v7, -v7, v10, v9
	v_div_fmas_f32 v7, v7, v8, v10
	v_div_fixup_f32 v228, v7, v6, v228
	ds_write_b32 v5, v228 offset:28
	s_waitcnt vmcnt(2)
	v_mul_f32_e32 v7, 0xbfb8aa3b, v229
	v_exp_f32_e32 v7, v7
	s_nop 0
	v_add_f32_e32 v6, 1.0, v7
	v_div_scale_f32 v7, s[34:35], v6, v6, v229
	v_rcp_f32_e32 v8, v7
	v_div_scale_f32 v9, vcc, v229, v6, v229
	v_fma_f32 v10, -v7, v8, 1.0
	v_fmac_f32_e32 v8, v10, v8
	v_mul_f32_e32 v10, v9, v8
	v_fma_f32 v11, -v7, v10, v9
	v_fmac_f32_e32 v10, v11, v8
	v_fma_f32 v7, -v7, v10, v9
	v_div_fmas_f32 v7, v7, v8, v10
	v_div_fixup_f32 v229, v7, v6, v229
	ds_write_b32 v5, v229 offset:16412
	s_waitcnt vmcnt(1)
	v_mul_f32_e32 v7, 0xbfb8aa3b, v230
	v_exp_f32_e32 v7, v7
	s_nop 0
	v_add_f32_e32 v6, 1.0, v7
	v_div_scale_f32 v7, s[34:35], v6, v6, v230
	v_rcp_f32_e32 v8, v7
	v_div_scale_f32 v9, vcc, v230, v6, v230
	v_fma_f32 v10, -v7, v8, 1.0
	v_fmac_f32_e32 v8, v10, v8
	v_mul_f32_e32 v10, v9, v8
	v_fma_f32 v11, -v7, v10, v9
	v_fmac_f32_e32 v10, v11, v8
	v_fma_f32 v7, -v7, v10, v9
	v_div_fmas_f32 v7, v7, v8, v10
	v_div_fixup_f32 v230, v7, v6, v230
	ds_write_b32 v5, v230 offset:32796
	s_waitcnt vmcnt(0)
	v_mul_f32_e32 v7, 0xbfb8aa3b, v231
	v_exp_f32_e32 v7, v7
	s_nop 0
	v_add_f32_e32 v6, 1.0, v7
	v_div_scale_f32 v7, s[34:35], v6, v6, v231
	v_rcp_f32_e32 v8, v7
	v_div_scale_f32 v9, vcc, v231, v6, v231
	v_fma_f32 v10, -v7, v8, 1.0
	v_fmac_f32_e32 v8, v10, v8
	v_mul_f32_e32 v10, v9, v8
	v_fma_f32 v11, -v7, v10, v9
	v_fmac_f32_e32 v10, v11, v8
	v_fma_f32 v7, -v7, v10, v9
	v_div_fmas_f32 v7, v7, v8, v10
	v_div_fixup_f32 v231, v7, v6, v231
	ds_write_b32 v5, v231 offset:49180
